# k17: k15 + grid barrier between attention and S5 output GEMM removed (S5 output units re-mapped block-local to the carry chain; sample out-projection moved behind the last grid barrier)
# speedup vs baseline: 1.0640x; 1.0232x over previous
; #define PG8_STAGE(bufoff, gbase, voff) do { _Pragma("unroll") for (int _i = 0; _i < 2; ++_i) \
;         __builtin_amdgcn_global_load_lds((const unsigned*)((const char*)(gbase) + (voff)[_i]), (LAS unsigned*)(lds + (bufoff) + ldsw + _i * 8192), 16, 0, 0); } while (0)
; #define PG8_WAIT_V(n) asm volatile("s_waitcnt vmcnt(" #n ")" ::: "memory")
; #define PG8_BAR __builtin_amdgcn_s_barrier()
;     __device__ bool next(int i, Unit& u) const {
;         const int L = i * G + c; if (L >= NG * (NCH / BM)) return false;
;         u.g = L / (NCH / BM); u.pm = L % (NCH / BM); u.pn = 0;
;         u.a = A + ((size_t)u.g * UXROWS + (size_t)u.pm * BM) * (UXR * 32); u.b = B + (size_t)u.g * wbytes; return true;
;     }
; template <class Epi, class Sched>
; __device__ __forceinline__ void gemm_phase(LAS unsigned char* lds, const Gemm g, const Sched& S, const Epi& E) {
;     ...
;     for (int i = 0; i < 2; ++i) { int R, C; stage_rc(tid * 16 + i * 8192, R, C); const int Rb = Epi::PERM ? ((R & ~31) + perm32(R & 31)) : R;
;         voffA[i] = (unsigned)R * g.lda + (g.aplane ? (unsigned)(C >> 4) * g.aplane + (unsigned)((C & 15) * 2) : (unsigned)(C * 2)); voffB[i] = (unsigned)Rb * g.ldb + (unsigned)(C * 2); }
;     const size_t kstepA = g.kstepA, kstepB = g.kstepB;
;     const size_t hstepA = (size_t)HALF * g.lda, hstepB = (size_t)HALF * g.ldb;
;     const unsigned ldsw = (unsigned)wid * 1024u;
;     const int aoff = lds_byte(wr * 64 + fr, fq * 8), boff = lds_byte(wc * 32 + fr, fq * 8);
;     ...
;     Unit cur, nxt; int ui = 0;
;     if (!S.next(0, cur)) return;
;     f32x4 acc[2][2][4][2];
; #pragma unroll
;     for (int a = 0; a < 2; ++a)
; #pragma unroll
;         for (int b = 0; b < 2; ++b)
; #pragma unroll
;             for (int m = 0; m < 4; ++m)
; #pragma unroll
;                 for (int n = 0; n < 2; ++n) acc[a][b][m][n] = (f32x4){0.f, 0.f, 0.f, 0.f};
;     bf16x8 At[4][2], B0[2][2], B1[2][2];
;     const char* cA = cur.a; const char* cB = cur.b;
;     PG8_WAIT_V(0);
;     PG8_STAGE(PG8_SB(0, 0), cB, voffB); PG8_STAGE(PG8_SB(0, 1), cB + hstepB, voffB); PG8_STAGE(PG8_SA(0, 0), cA, voffA); PG8_STAGE(PG8_SA(0, 1), cA + hstepA, voffA);
;     if (wr == 1) PG8_BAR;
;     PG8_WAIT_V(2); PG8_BAR;
;     PG8_STAGE(PG8_SB(1, 0), cB + kstepB, voffB); PG8_STAGE(PG8_SA(1, 0), cA + kstepA, voffA); PG8_STAGE(PG8_SB(1, 1), cB + hstepB + kstepB, voffB);
;     PG8_WAIT_V(6); PG8_BAR;
.LBB0_884:
	s_or_b64 exec, exec, s[4:5]
	v_writelane_b32 v255, s38, 44
	v_writelane_b32 v255, s39, 45
	s_waitcnt lgkmcnt(0)
	s_barrier
.LBB0_894:
	s_and_b32 s16, s2, 31
	s_lshr_b32 s88, s2, 5
	s_lshl_b32 s88, s88, 1
	s_mul_i32 s0, s16, 0x306000
	s_mul_i32 s1, s88, 0x30000
	s_add_u32 s30, s22, s0
	s_addc_u32 s31, s23, 0
	s_add_u32 s30, s30, s1
	s_addc_u32 s31, s31, 0
	v_readlane_b32 s0, v255, 20
	s_add_u32 s4, s92, 0x2b400000
	v_mov_b32_e32 v8, v208
	v_readlane_b32 s1, v255, 21
	v_readlane_b32 s66, v255, 24
	s_addc_u32 s5, s93, 0
	s_and_b64 vcc, exec, s[0:1]
	v_readfirstlane_b32 s10, v8
	v_readlane_b32 s64, v255, 23
	v_readlane_b32 s67, v255, 25
	s_cbranch_vccz .LBB0_908
	v_lshlrev_b32_e32 v1, 4, v8
	v_add_u32_e32 v0, 0x2000, v1
	v_ashrrev_i32_e32 v2, 31, v0
	v_lshrrev_b32_e32 v2, 22, v2
	v_add_u32_e32 v2, v0, v2
	v_ashrrev_i32_e32 v2, 10, v2
	v_mul_i32_i24_e32 v3, 0x400, v2
	v_sub_u32_e32 v0, v0, v3
	v_lshrrev_b32_e32 v3, 4, v0
	v_bitop3_b32 v0, v3, v0, 32 bitop3:0x6c
	v_ashrrev_i32_e32 v3, 31, v0
	v_lshrrev_b32_e32 v3, 26, v3
	v_add_u32_e32 v3, v0, v3
	v_lshlrev_b32_e32 v5, 3, v2
	v_ashrrev_i32_e32 v4, 6, v3
	v_and_b32_e32 v5, -16, v5
	v_and_b32_e32 v3, 0xc0, v3
	v_add_u32_e32 v5, v4, v5
	v_sub_u32_e32 v0, v0, v3
	v_mov_b32_e32 v3, 1
	v_and_b32_e32 v4, 3, v4
	s_mov_b32 s13, 0xffffe0
	v_lshrrev_b32_e32 v6, 2, v5
	v_lshlrev_b32_e32 v7, 1, v5
	v_lshlrev_b32_e32 v2, 5, v2
	v_ashrrev_i16_sdwa v0, v3, sext(v0) dst_sel:DWORD dst_unused:UNUSED_PAD src0_sel:DWORD src1_sel:BYTE_0
	v_and_or_b32 v4, v5, s13, v4
	v_and_b32_e32 v6, 4, v6
	v_and_b32_e32 v7, 24, v7
	v_and_b32_e32 v2, 32, v2
	v_bfe_i32 v0, v0, 0, 16
	v_or3_b32 v4, v4, v6, v7
	v_add_lshl_u32 v0, v2, v0, 1
	s_movk_i32 s20, 0x300
	v_mad_u32_u24 v128, v4, s20, v0
	v_mad_u64_u32 v[130:131], s[8:9], v5, s20, v[0:1]
	v_bfe_i32 v0, v8, 27, 1
	v_lshrrev_b32_e32 v0, 22, v0
	v_add_u32_e32 v0, v1, v0
	v_and_b32_e32 v0, 0xfffffc00, v0
	v_sub_u32_e32 v0, v1, v0
	v_lshrrev_b32_e32 v1, 4, v0
	v_ashrrev_i32_e32 v4, 31, v8
	v_bitop3_b32 v0, v1, v0, 32 bitop3:0x6c
	v_lshrrev_b32_e32 v4, 26, v4
	v_ashrrev_i32_e32 v1, 31, v0
	v_add_u32_e32 v4, v8, v4
	s_mul_i32 s1, s16, 0x30000
	v_readlane_b32 s14, v255, 12
	v_lshrrev_b32_e32 v1, 26, v1
	v_ashrrev_i32_e32 v4, 6, v4
	s_mul_hi_i32 s0, s16, 0x30000
	s_add_u32 s42, s14, s1
	v_readlane_b32 s15, v255, 13
	v_add_u32_e32 v1, v0, v1
	v_lshlrev_b32_e32 v5, 3, v4
	s_addc_u32 s43, s15, s0
	s_ashr_i32 s12, s10, 6
	v_ashrrev_i32_e32 v2, 6, v1
	v_and_b32_e32 v5, -16, v5
	v_and_b32_e32 v1, 0xc0, v1
	s_ashr_i32 s11, s10, 8
	s_lshl_b32 s17, s12, 10
	v_add_u32_e32 v5, v2, v5
	v_sub_u32_e32 v0, v0, v1
	s_add_u32 s0, s30, 0x18000
	v_and_b32_e32 v2, 3, v2
	v_lshrrev_b32_e32 v6, 2, v5
	v_lshlrev_b32_e32 v7, 1, v5
	v_lshlrev_b32_e32 v4, 5, v4
	v_ashrrev_i16_sdwa v0, v3, sext(v0) dst_sel:DWORD dst_unused:UNUSED_PAD src0_sel:DWORD src1_sel:BYTE_0
	s_addc_u32 s1, s31, 0
	v_and_or_b32 v2, v5, s13, v2
	v_and_b32_e32 v6, 4, v6
	v_and_b32_e32 v7, 24, v7
	v_and_b32_e32 v4, 32, v4
	v_bfe_i32 v0, v0, 0, 16
	s_add_u32 s6, s42, 0x18000
	v_or3_b32 v2, v2, v6, v7
	v_add_lshl_u32 v0, v4, v0, 1
	s_addc_u32 s7, s43, 0
	v_mad_u32_u24 v132, v2, s20, v0
	v_mad_u64_u32 v[134:135], s[8:9], v5, s20, v[0:1]
	s_add_i32 s20, s17, 0
	s_waitcnt vmcnt(0)
	s_add_i32 m0, s20, 0x10000
	s_add_i32 s21, s20, 0x2000
	global_load_lds_dwordx4 v132, s[42:43]
	s_add_i32 m0, s20, 0x12000
	s_add_i32 s44, s20, 0x4000
	global_load_lds_dwordx4 v128, s[42:43]
	s_add_i32 m0, s20, 0x14000
	s_add_i32 s45, s20, 0x6000
	global_load_lds_dwordx4 v132, s[6:7]
	s_add_i32 m0, s20, 0x16000
	v_mov_b32_e32 v137, 0
	global_load_lds_dwordx4 v128, s[6:7]
	s_mov_b32 m0, s20
	v_mov_b32_e32 v133, v137
	global_load_lds_dwordx4 v134, s[30:31]
	s_mov_b32 m0, s21
	v_mov_b32_e32 v129, v137
	global_load_lds_dwordx4 v130, s[30:31]
	s_mov_b32 m0, s44
	v_mov_b32_e32 v135, v137
	global_load_lds_dwordx4 v134, s[0:1]
	s_mov_b32 m0, s45
	v_mov_b32_e32 v131, v137
	global_load_lds_dwordx4 v130, s[0:1]
	s_cmp_eq_u32 s11, 1
	v_lshl_add_u64 v[6:7], s[42:43], 0, v[132:133]
	v_lshl_add_u64 v[4:5], s[42:43], 0, v[128:129]
	v_lshl_add_u64 v[0:1], s[30:31], 0, v[134:135]
	s_cselect_b64 s[6:7], -1, 0
	s_cmp_lg_u32 s11, 1
	v_lshl_add_u64 v[2:3], s[30:31], 0, v[130:131]
	s_cbranch_scc1 .LBB0_897
	s_barrier

;     __device__ bool next(int i, Unit& u) const {
;         const int L = i * G + c; if (L >= NG * (NCH / BM)) return false;
;         u.g = L / (NCH / BM); u.pm = L % (NCH / BM); u.pn = 0;
;         u.a = A + ((size_t)u.g * UXROWS + (size_t)u.pm * BM) * (UXR * 32); u.b = B + (size_t)u.g * wbytes; return true;
;     }
.LBB0_900:
	s_cmpk_lt_i32 s48, 0x200
	s_cselect_b64 s[38:39], -1, 0
	s_cmpk_gt_i32 s48, 0x1ff
	s_cbranch_scc1 .LBB0_902
	s_and_b32 s59, s48, 31
	s_bfe_u32 s17, s48, 0x30005
	s_lshl_b32 s17, s17, 1
	s_lshr_b32 s60, s48, 8
	s_add_i32 s60, s60, s17
	s_mul_i32 s29, s60, 0x30000
	s_mul_i32 s28, s59, 0x306000
	s_ashr_i32 s34, s29, 31
	s_mul_hi_i32 s17, s59, 0x306000
	s_add_u32 s28, s22, s28
	s_addc_u32 s17, s23, s17
	s_add_u32 s28, s28, s29
	s_addc_u32 s29, s17, s34
	s_mul_i32 s34, s59, 0x30000
	s_mul_hi_i32 s17, s59, 0x30000
	s_add_u32 s34, s14, s34
	s_addc_u32 s35, s15, s17

; #define LAS __attribute__((address_space(3)))
; __device__ __forceinline__ int fresh_tid() { int t = threadIdx.x; asm volatile("" : "+v"(t)); return t; }
; #define GRID_BAR() xcd_barrier(xbar)
; __global__ void __launch_bounds__(NTHR, 2) hymba_fwd(Params P) {
;     ...
;     GRID_BAR();
;     for (int it = blk; it < 256; it += G) {
;         const int mb = it & 15, ns = it >> 4;
;         LAS float* Cs = (LAS float*)lds; constexpr int ldc = 68;
;         __syncthreads();
;         skinny32(Cs, MX + (size_t)(PT + 32 * mb) * DM, DM, WOUT, DM, 64, DM, [&](int ct) { return 64 * ns + 16 * ct; });
;         const int tid = fresh_tid();
.LBB0_1034:
	s_or_b64 exec, exec, s[0:1]
	s_waitcnt lgkmcnt(0)
	s_barrier
	v_readlane_b32 s38, v255, 44
	v_readlane_b32 s39, v255, 45
	s_add_u32 s0, s90, 0x10000000
	s_addc_u32 s1, s91, 0
	s_mov_b32 s5, 0
	v_mov_b32_e32 v73, 0
	s_mov_b64 s[6:7], 0x9800000
	s_mov_b64 s[8:9], 0x9808000
	s_movk_i32 s17, 0x110
	s_mov_b64 s[10:11], 0x9808040
	s_mov_b64 s[12:13], 0x9808080
	s_mov_b64 s[24:25], 0x98080c0
	s_mov_b64 s[26:27], 0x9808100
	s_mov_b64 s[28:29], 0x9808140
	s_mov_b64 s[34:35], 0x9808180
	s_mov_b64 s[42:43], 0x98081c0
	s_mov_b32 s20, 0x9800000
	s_movk_i32 s21, 0x100
	s_mov_b64 s[44:45], 0x80
	s_mov_b64 s[46:47], 0xc0
	s_mov_b64 s[48:49], 0x100
	s_mov_b64 s[54:55], 0x140
	s_mov_b64 s[56:57], 0x180
	s_mov_b64 s[58:59], 0x1c0
	s_movk_i32 s50, 0x3000
	s_mov_b64 s[60:61], 0x102000
	s_mov_b32 s51, 0x102000
	s_mov_b32 s52, s2
	s_branch .LBB0_887

; #define PG8_STAGE(bufoff, gbase, voff) do { _Pragma("unroll") for (int _i = 0; _i < 2; ++_i) \
;         __builtin_amdgcn_global_load_lds((const unsigned*)((const char*)(gbase) + (voff)[_i]), (LAS unsigned*)(lds + (bufoff) + ldsw + _i * 8192), 16, 0, 0); } while (0)
; #define PG8_WAIT_V(n) asm volatile("s_waitcnt vmcnt(" #n ")" ::: "memory")
; template <class Epi, class Sched>
; __device__ __forceinline__ void gemm_phase(LAS unsigned char* lds, const Gemm g, const Sched& S, const Epi& E) {
;     ...
;     for (int i = 0; i < 2; ++i) { int R, C; stage_rc(tid * 16 + i * 8192, R, C); const int Rb = Epi::PERM ? ((R & ~31) + perm32(R & 31)) : R;
;         voffA[i] = (unsigned)R * g.lda + (g.aplane ? (unsigned)(C >> 4) * g.aplane + (unsigned)((C & 15) * 2) : (unsigned)(C * 2)); voffB[i] = (unsigned)Rb * g.ldb + (unsigned)(C * 2); }
;     const size_t kstepA = g.kstepA, kstepB = g.kstepB;
;     const size_t hstepA = (size_t)HALF * g.lda, hstepB = (size_t)HALF * g.ldb;
;     const unsigned ldsw = (unsigned)wid * 1024u;
;     const int aoff = lds_byte(wr * 64 + fr, fq * 8), boff = lds_byte(wc * 32 + fr, fq * 8);
;     ...
;     Unit cur, nxt; int ui = 0;
;     if (!S.next(0, cur)) return;
;     f32x4 acc[2][2][4][2];
; #pragma unroll
;     for (int a = 0; a < 2; ++a)
; #pragma unroll
;         for (int b = 0; b < 2; ++b)
; #pragma unroll
;             for (int m = 0; m < 4; ++m)
; #pragma unroll
;                 for (int n = 0; n < 2; ++n) acc[a][b][m][n] = (f32x4){0.f, 0.f, 0.f, 0.f};
;     bf16x8 At[4][2], B0[2][2], B1[2][2];
;     const char* cA = cur.a; const char* cB = cur.b;
;     PG8_WAIT_V(0);
;     PG8_STAGE(PG8_SB(0, 0), cB, voffB); PG8_STAGE(PG8_SB(0, 1), cB + hstepB, voffB); PG8_STAGE(PG8_SA(0, 0), cA, voffA); PG8_STAGE(PG8_SA(0, 1), cA + hstepA, voffA);
;     if (wr == 1) PG8_BAR;
;     PG8_WAIT_V(2); PG8_BAR;
;     PG8_STAGE(PG8_SB(1, 0), cB + kstepB, voffB); PG8_STAGE(PG8_SA(1, 0), cA + kstepA, voffA); PG8_STAGE(PG8_SB(1, 1), cB + hstepB + kstepB, voffB);
;     PG8_WAIT_V(6); PG8_BAR;
; __global__ void __launch_bounds__(NTHR, 2) hymba_fwd(Params P) {
;     ...
;     for (int rep = 0; rep < REP_P7; ++rep) {
;         pg8::Gemm g{DM * 2, DM * 2, 128, 128, DM / 64, 0}; pg8::StaticOrder S; S.init(PT, DM, G, blk, MX, WOUT, DM * 2, DM * 2);
;         EpiOut E{P.x_prompt, P.x_sample, MOD, out + O_YP, out + O_YS};
;         pg8::gemm_phase<EpiOut, pg8::StaticOrder>(lds, g, S, E);
.Lmy_op_done:
	v_readlane_b32 s64, v255, 23
	v_readlane_b32 s66, v255, 24
	v_readlane_b32 s67, v255, 25
	s_cmpk_lt_i32 s2, 0x400
	s_nop 0
	v_readfirstlane_b32 s1, v208
	s_cbranch_scc0 .LBB0_1054
	v_lshlrev_b32_e32 v0, 4, v208
	v_add_u32_e32 v1, 0x2000, v0
	v_ashrrev_i32_e32 v2, 31, v1
	v_lshrrev_b32_e32 v2, 22, v2
	v_add_u32_e32 v2, v1, v2
	v_ashrrev_i32_e32 v8, 10, v2
	v_mul_i32_i24_e32 v3, 0x400, v8
	v_sub_u32_e32 v1, v1, v3
	v_lshrrev_b32_e32 v3, 4, v1
	v_bitop3_b32 v1, v3, v1, 32 bitop3:0x6c
	v_ashrrev_i32_e32 v3, 31, v1
	v_lshrrev_b32_e32 v3, 26, v3
	v_add_u32_e32 v3, v1, v3
	s_ashr_i32 s6, s1, 6
	v_ashrrev_i32_e32 v9, 6, v3
	v_and_b32_e32 v3, 0xc0, v3
	s_ashr_i32 s7, s1, 8
	s_lshl_b32 s46, s6, 10
	v_sub_u32_e32 v1, v1, v3
	v_mov_b32_e32 v3, 1
	s_lshl_b32 s8, s64, 7
	v_lshlrev_b32_e32 v2, 5, v8
	v_ashrrev_i16_sdwa v1, v3, sext(v1) dst_sel:DWORD dst_unused:UNUSED_PAD src0_sel:DWORD src1_sel:BYTE_0
	s_mul_i32 s0, s64, 0x81
	s_and_b64 s[4:5], s[66:67], exec
	v_and_b32_e32 v2, 32, v2
	v_bfe_i32 v10, v1, 0, 16
	s_cselect_b32 s0, s0, s8
	v_readlane_b32 s4, v255, 22
	v_add_u32_e32 v1, v2, v10
	v_lshlrev_b32_e32 v2, 3, v8
	s_add_i32 s0, s0, s4
	v_and_b32_e32 v2, 0x1ffff0, v2
	s_ashr_i32 s4, s0, 31
	v_add_lshl_u32 v2, v9, v2, 11
	s_lshr_b32 s4, s4, 27
	v_lshl_add_u32 v144, v1, 1, v2
	v_bfe_i32 v2, v208, 27, 1
	s_add_i32 s4, s0, s4
	v_lshrrev_b32_e32 v2, 22, v2
	s_ashr_i32 s5, s4, 5
	s_and_b32 s4, s4, 0xffe0
	v_add_u32_e32 v2, v0, v2
	s_sub_i32 s4, s0, s4
	v_and_b32_e32 v2, 0xfffffc00, v2
	s_bfe_i32 s0, s4, 0x80000
	v_sub_u32_e32 v0, v0, v2
	s_bfe_u32 s0, s0, 0x3000c
	v_lshrrev_b32_e32 v2, 4, v0
	s_add_i32 s8, s4, s0
	v_bitop3_b32 v0, v2, v0, 32 bitop3:0x6c
	s_bfe_i32 s0, s8, 0x80000
	s_and_b32 s8, s8, 0xf8
	v_ashrrev_i32_e32 v2, 31, v0
	s_sub_i32 s4, s4, s8
	v_ashrrev_i32_e32 v1, 31, v208
	v_lshrrev_b32_e32 v2, 26, v2
	s_lshl_b32 s5, s5, 3
	s_sext_i32_i8 s4, s4
	v_lshrrev_b32_e32 v1, 26, v1
	v_add_u32_e32 v2, v0, v2
	s_add_i32 s34, s5, s4
	v_add_u32_e32 v1, v208, v1
	v_ashrrev_i32_e32 v12, 6, v2
	v_and_b32_e32 v2, 0xc0, v2
	s_sext_i32_i16 s0, s0
	s_ashr_i32 s35, s34, 31
	v_ashrrev_i32_e32 v11, 6, v1
	v_sub_u32_e32 v0, v0, v2
	s_lshr_b32 s0, s0, 3
	s_lshl_b64 s[4:5], s[34:35], 19
	v_lshlrev_b32_e32 v1, 5, v11
	v_ashrrev_i16_sdwa v0, v3, sext(v0) dst_sel:DWORD dst_unused:UNUSED_PAD src0_sel:DWORD src1_sel:BYTE_0
	s_add_u32 s38, s40, s4
	v_and_b32_e32 v1, 32, v1
	v_bfe_i32 v13, v0, 0, 16
	s_addc_u32 s39, s41, s5
	s_bfe_i64 s[4:5], s[0:1], 0x100000
	v_add_u32_e32 v0, v1, v13
	v_lshlrev_b32_e32 v1, 3, v11
	s_lshl_b64 s[4:5], s[4:5], 19
	v_and_b32_e32 v1, 0x1ffff0, v1
	s_add_u32 s42, s96, s4
	v_add_lshl_u32 v1, v12, v1, 11
	s_addc_u32 s43, s97, s5
	s_add_i32 s35, s46, 0
	v_lshl_add_u32 v146, v0, 1, v1
	s_waitcnt vmcnt(0)
	s_add_i32 m0, s35, 0x10000
	v_mov_b32_e32 v147, 0
	global_load_lds_dwordx4 v146, s[42:43]
	s_add_i32 m0, s35, 0x12000
	s_add_u32 s4, s42, 0x40000
	global_load_lds_dwordx4 v144, s[42:43]
	s_addc_u32 s5, s43, 0
	s_add_i32 m0, s35, 0x14000
	s_add_i32 s47, s35, 0x2000
	global_load_lds_dwordx4 v146, s[4:5]
	s_add_i32 m0, s35, 0x16000
	v_mov_b32_e32 v145, v147
	global_load_lds_dwordx4 v144, s[4:5]
	s_mov_b32 m0, s35
	s_add_u32 s4, s38, 0x40000
	global_load_lds_dwordx4 v146, s[38:39]
	s_mov_b32 m0, s47
	s_addc_u32 s5, s39, 0
	s_add_i32 s48, s35, 0x4000
	global_load_lds_dwordx4 v144, s[38:39]
	s_mov_b32 m0, s48
	s_add_i32 s49, s35, 0x6000
	global_load_lds_dwordx4 v146, s[4:5]
	s_mov_b32 m0, s49
	s_cmp_eq_u32 s7, 1
	global_load_lds_dwordx4 v144, s[4:5]
	s_mov_b32 s50, 0
	v_lshl_add_u64 v[6:7], s[42:43], 0, v[146:147]
	v_lshl_add_u64 v[4:5], s[42:43], 0, v[144:145]
	v_lshl_add_u64 v[0:1], s[38:39], 0, v[146:147]
	s_cselect_b64 s[4:5], -1, 0
	s_cmp_lg_u32 s7, 1
	v_lshl_add_u64 v[2:3], s[38:39], 0, v[144:145]
	s_cbranch_scc1 .LBB0_1037
	s_barrier
